# dsa_topk only: permlane16/32_swap exchanges in score loop, emit pass with one pair of LDS atomics per trip, rank pass 8 entries per trip; attention K-gather change dropped
# speedup vs baseline: 1.0092x; 1.0022x over previous
; __device__ __forceinline__ int shi(int v, int src) { return __builtin_amdgcn_ds_bpermute(src << 2, v); }
; __device__ __forceinline__ void dsa_attn(const bf16_t* DP, const int* SEL, bf16_t* O, LAS unsigned char* lds, int widk) {
;     ...
;         int s0 = SEL[tok * 256 + lane], s1 = SEL[tok * 256 + 64 + lane], s2 = SEL[tok * 256 + 128 + lane], s3 = SEL[tok * 256 + 192 + lane];
;         s0 = s0 < 0 ? 0 : s0; s1 = s1 < 0 ? 0 : s1; s2 = s2 < 0 ? 0 : s2; s3 = s3 < 0 ? 0 : s3;
;         bf16x8 qf[4];
; #pragma unroll
;         for (int ks = 0; ks < 4; ++ks) { qf[ks] = (bf16x8){0, 0, 0, 0, 0, 0, 0, 0}; if (fr < 4) qf[ks] = *(const bf16x8*)(DP + tok * DSA_NP + (g * 4 + fr) * 128 + ks * 32 + fq * 8); }
;         const bf16_t* kbase = DP + (size_t)b * SEQ * DSA_NP + 2048 + g * 128 + fq * 8;
;         f32x4 acc[16];
; #pragma unroll
;         for (int j = 0; j < 16; ++j) {
;             const int sreg = (j < 4) ? s0 : (j < 8) ? s1 : (j < 12) ? s2 : s3;
;             const int idx = shi(sreg, (16 * j + fr) & 63);
;             const bf16_t* kr = kbase + (size_t)idx * DSA_NP;
;             const bf16x8 a0 = *(const bf16x8*)kr, a1 = *(const bf16x8*)(kr + 32), a2 = *(const bf16x8*)(kr + 64), a3 = *(const bf16x8*)(kr + 96);
;             f32x4 a = {0.f, 0.f, 0.f, 0.f};
;             a = __builtin_amdgcn_mfma_f32_16x16x32_bf16(a0, qf[0], a, 0, 0, 0);
;             a = __builtin_amdgcn_mfma_f32_16x16x32_bf16(a1, qf[1], a, 0, 0, 0);
;             a = __builtin_amdgcn_mfma_f32_16x16x32_bf16(a2, qf[2], a, 0, 0, 0);
;             a = __builtin_amdgcn_mfma_f32_16x16x32_bf16(a3, qf[3], a, 0, 0, 0);
;             acc[j] = a;
;             if ((j & 7) == 7) asm volatile("" ::: "memory");
;         }
.LBB0_671:
	s_or_b64 exec, exec, s[6:7]
	s_mulk_i32 s14, 0x2200
	s_waitcnt vmcnt(3)
	v_max_i32_e32 v34, 0, v21
	s_add_u32 s6, s44, s14
	s_waitcnt vmcnt(2)
	v_max_i32_e32 v135, 0, v20
	s_addc_u32 s7, s45, 0
	ds_bpermute_b32 v20, v143, v34
	s_add_u32 s6, s6, s12
	s_addc_u32 s7, s7, 0
	v_lshl_add_u64 v[18:19], s[6:7], 0, v[0:1]
	s_mov_b64 s[14:15], 0x1000
	v_lshl_add_u64 v[18:19], v[18:19], 0, s[14:15]
	s_waitcnt lgkmcnt(0)
	v_mad_i64_i32 v[32:33], s[14:15], v20, s62, v[18:19]
	s_waitcnt vmcnt(1)
	v_max_i32_e32 v134, 0, v23
	s_waitcnt vmcnt(0)
	v_max_i32_e32 v241, 0, v22
	global_load_dwordx4 v[20:23], v[32:33], off
	global_load_dwordx4 v[24:27], v[32:33], off offset:64
	global_load_dwordx4 v[28:31], v[32:33], off offset:128
	global_load_dwordx4 v[36:39], v[32:33], off offset:192
	v_mov_b32_e32 v149, v1
	v_or_b32_e32 v130, 2, v167
	s_waitcnt vmcnt(3)
	v_mfma_f32_16x16x32_bf16 v[20:23], v[20:23], v[6:9], 0
	s_waitcnt vmcnt(2)
	v_mfma_f32_16x16x32_bf16 v[20:23], v[24:27], v[2:5], v[20:23]
	s_waitcnt vmcnt(1)
	v_mfma_f32_16x16x32_bf16 v[20:23], v[28:31], v[14:17], v[20:23]
	s_waitcnt vmcnt(0)
	v_mfma_f32_16x16x32_bf16 v[66:69], v[36:39], v[10:13], v[20:23]
	s_nop 5
	ds_bpermute_b32 v20, v172, v34
	s_nop 0
	v_mul_f32_e32 v66, 0x3db504f3, v66
	v_mul_f32_e32 v67, 0x3db504f3, v67
	v_mul_f32_e32 v68, 0x3db504f3, v68
	s_waitcnt lgkmcnt(0)
	v_mad_i64_i32 v[32:33], s[14:15], v20, s62, v[18:19]
	global_load_dwordx4 v[20:23], v[32:33], off
	global_load_dwordx4 v[24:27], v[32:33], off offset:64
	global_load_dwordx4 v[28:31], v[32:33], off offset:128
	global_load_dwordx4 v[36:39], v[32:33], off offset:192
	s_waitcnt vmcnt(3)
	v_mfma_f32_16x16x32_bf16 v[20:23], v[20:23], v[6:9], 0
	s_waitcnt vmcnt(2)
	v_mfma_f32_16x16x32_bf16 v[20:23], v[24:27], v[2:5], v[20:23]
	s_waitcnt vmcnt(1)
	v_mfma_f32_16x16x32_bf16 v[20:23], v[28:31], v[14:17], v[20:23]
	s_waitcnt vmcnt(0)
	v_mfma_f32_16x16x32_bf16 v[70:73], v[36:39], v[10:13], v[20:23]
	s_nop 5
	ds_bpermute_b32 v20, v173, v34
	s_waitcnt lgkmcnt(0)
	v_mad_i64_i32 v[32:33], s[14:15], v20, s62, v[18:19]
	global_load_dwordx4 v[20:23], v[32:33], off
	global_load_dwordx4 v[24:27], v[32:33], off offset:64
	global_load_dwordx4 v[28:31], v[32:33], off offset:128
	global_load_dwordx4 v[36:39], v[32:33], off offset:192
	s_waitcnt vmcnt(3)
	v_mfma_f32_16x16x32_bf16 v[20:23], v[20:23], v[6:9], 0
	s_waitcnt vmcnt(2)
	v_mfma_f32_16x16x32_bf16 v[20:23], v[24:27], v[2:5], v[20:23]
	s_waitcnt vmcnt(1)
	v_mfma_f32_16x16x32_bf16 v[20:23], v[28:31], v[14:17], v[20:23]
	s_waitcnt vmcnt(0)
	v_mfma_f32_16x16x32_bf16 v[74:77], v[36:39], v[10:13], v[20:23]
	s_nop 5
	ds_bpermute_b32 v20, v174, v34
	s_waitcnt lgkmcnt(0)
	v_mad_i64_i32 v[32:33], s[14:15], v20, s62, v[18:19]
	global_load_dwordx4 v[20:23], v[32:33], off
	global_load_dwordx4 v[24:27], v[32:33], off offset:64
	global_load_dwordx4 v[28:31], v[32:33], off offset:128
	global_load_dwordx4 v[36:39], v[32:33], off offset:192
	s_waitcnt vmcnt(3)
	v_mfma_f32_16x16x32_bf16 v[20:23], v[20:23], v[6:9], 0
	s_waitcnt vmcnt(2)
	v_mfma_f32_16x16x32_bf16 v[20:23], v[24:27], v[2:5], v[20:23]
	s_waitcnt vmcnt(1)
	v_mfma_f32_16x16x32_bf16 v[20:23], v[28:31], v[14:17], v[20:23]
	s_waitcnt vmcnt(0)
	v_mfma_f32_16x16x32_bf16 v[78:81], v[36:39], v[10:13], v[20:23]
	s_nop 5
	ds_bpermute_b32 v20, v143, v135
	s_waitcnt lgkmcnt(0)
	v_mad_i64_i32 v[32:33], s[14:15], v20, s62, v[18:19]
	global_load_dwordx4 v[20:23], v[32:33], off
	global_load_dwordx4 v[24:27], v[32:33], off offset:64
	global_load_dwordx4 v[28:31], v[32:33], off offset:128
	global_load_dwordx4 v[36:39], v[32:33], off offset:192
	s_waitcnt vmcnt(3)
	v_mfma_f32_16x16x32_bf16 v[20:23], v[20:23], v[6:9], 0
	s_waitcnt vmcnt(2)
	v_mfma_f32_16x16x32_bf16 v[20:23], v[24:27], v[2:5], v[20:23]
	s_waitcnt vmcnt(1)
	v_mfma_f32_16x16x32_bf16 v[20:23], v[28:31], v[14:17], v[20:23]
	s_waitcnt vmcnt(0)
	v_mfma_f32_16x16x32_bf16 v[82:85], v[36:39], v[10:13], v[20:23]
	s_nop 5
	ds_bpermute_b32 v20, v172, v135
	s_waitcnt lgkmcnt(0)
	v_mad_i64_i32 v[32:33], s[14:15], v20, s62, v[18:19]
	global_load_dwordx4 v[20:23], v[32:33], off
	global_load_dwordx4 v[24:27], v[32:33], off offset:64
	global_load_dwordx4 v[28:31], v[32:33], off offset:128
	global_load_dwordx4 v[36:39], v[32:33], off offset:192
	s_waitcnt vmcnt(3)
	v_mfma_f32_16x16x32_bf16 v[20:23], v[20:23], v[6:9], 0
	s_waitcnt vmcnt(2)
	v_mfma_f32_16x16x32_bf16 v[20:23], v[24:27], v[2:5], v[20:23]
	s_waitcnt vmcnt(1)
	v_mfma_f32_16x16x32_bf16 v[20:23], v[28:31], v[14:17], v[20:23]
	s_waitcnt vmcnt(0)
	v_mfma_f32_16x16x32_bf16 v[86:89], v[36:39], v[10:13], v[20:23]
	s_nop 5
	ds_bpermute_b32 v20, v173, v135
	s_waitcnt lgkmcnt(0)
	v_mad_i64_i32 v[32:33], s[14:15], v20, s62, v[18:19]
	global_load_dwordx4 v[20:23], v[32:33], off
	global_load_dwordx4 v[24:27], v[32:33], off offset:64
	global_load_dwordx4 v[28:31], v[32:33], off offset:128
	global_load_dwordx4 v[36:39], v[32:33], off offset:192
	s_waitcnt vmcnt(3)
	v_mfma_f32_16x16x32_bf16 v[20:23], v[20:23], v[6:9], 0
	s_waitcnt vmcnt(2)
	v_mfma_f32_16x16x32_bf16 v[20:23], v[24:27], v[2:5], v[20:23]
	s_waitcnt vmcnt(1)
	v_mfma_f32_16x16x32_bf16 v[20:23], v[28:31], v[14:17], v[20:23]
	s_waitcnt vmcnt(0)
	v_mfma_f32_16x16x32_bf16 v[90:93], v[36:39], v[10:13], v[20:23]
	s_nop 5
	ds_bpermute_b32 v20, v174, v135
	s_waitcnt lgkmcnt(0)
	v_mad_i64_i32 v[32:33], s[14:15], v20, s62, v[18:19]
	global_load_dwordx4 v[20:23], v[32:33], off
	global_load_dwordx4 v[24:27], v[32:33], off offset:64
	global_load_dwordx4 v[28:31], v[32:33], off offset:128
	global_load_dwordx4 v[36:39], v[32:33], off offset:192
	s_waitcnt vmcnt(3)
	v_mfma_f32_16x16x32_bf16 v[20:23], v[20:23], v[6:9], 0
	s_waitcnt vmcnt(2)
; __device__ __forceinline__ int shi(int v, int src) { return __builtin_amdgcn_ds_bpermute(src << 2, v); }
; __device__ __forceinline__ void dsa_attn(const bf16_t* DP, const int* SEL, bf16_t* O, LAS unsigned char* lds, int widk) {
;     ...
;         for (int j = 0; j < 16; ++j) {
;             const int sreg = (j < 4) ? s0 : (j < 8) ? s1 : (j < 12) ? s2 : s3;
;             const int idx = shi(sreg, (16 * j + fr) & 63);
;             const bf16_t* kr = kbase + (size_t)idx * DSA_NP;
;             const bf16x8 a0 = *(const bf16x8*)kr, a1 = *(const bf16x8*)(kr + 32), a2 = *(const bf16x8*)(kr + 64), a3 = *(const bf16x8*)(kr + 96);
;             f32x4 a = {0.f, 0.f, 0.f, 0.f};
;             a = __builtin_amdgcn_mfma_f32_16x16x32_bf16(a0, qf[0], a, 0, 0, 0);
;             a = __builtin_amdgcn_mfma_f32_16x16x32_bf16(a1, qf[1], a, 0, 0, 0);
;             a = __builtin_amdgcn_mfma_f32_16x16x32_bf16(a2, qf[2], a, 0, 0, 0);
;             a = __builtin_amdgcn_mfma_f32_16x16x32_bf16(a3, qf[3], a, 0, 0, 0);
;             acc[j] = a;
;             if ((j & 7) == 7) asm volatile("" ::: "memory");
;         }
;         const bf16_t* vbase = DP + (size_t)b * SEQ * DSA_NP + 2560 + g * 128 + fr * 8;
;         u32x4 vcur[8], vnxt[8], vnn[8];
	v_mfma_f32_16x16x32_bf16 v[20:23], v[24:27], v[2:5], v[20:23]
	s_waitcnt vmcnt(1)
	v_mfma_f32_16x16x32_bf16 v[20:23], v[28:31], v[14:17], v[20:23]
	s_waitcnt vmcnt(0)
	v_mfma_f32_16x16x32_bf16 v[94:97], v[36:39], v[10:13], v[20:23]
	s_nop 5
	ds_bpermute_b32 v20, v143, v134
	s_waitcnt lgkmcnt(0)
	v_mad_i64_i32 v[32:33], s[14:15], v20, s62, v[18:19]
	global_load_dwordx4 v[20:23], v[32:33], off
	global_load_dwordx4 v[24:27], v[32:33], off offset:64
	global_load_dwordx4 v[28:31], v[32:33], off offset:128
	global_load_dwordx4 v[36:39], v[32:33], off offset:192
	s_waitcnt vmcnt(3)
	v_mfma_f32_16x16x32_bf16 v[20:23], v[20:23], v[6:9], 0
	s_waitcnt vmcnt(2)
	v_mfma_f32_16x16x32_bf16 v[20:23], v[24:27], v[2:5], v[20:23]
	s_waitcnt vmcnt(1)
	v_mfma_f32_16x16x32_bf16 v[20:23], v[28:31], v[14:17], v[20:23]
	s_waitcnt vmcnt(0)
	v_mfma_f32_16x16x32_bf16 v[98:101], v[36:39], v[10:13], v[20:23]
	s_nop 5
	ds_bpermute_b32 v20, v172, v134
	s_waitcnt lgkmcnt(0)
	v_mad_i64_i32 v[32:33], s[14:15], v20, s62, v[18:19]
	global_load_dwordx4 v[20:23], v[32:33], off
	global_load_dwordx4 v[24:27], v[32:33], off offset:64
	global_load_dwordx4 v[28:31], v[32:33], off offset:128
	global_load_dwordx4 v[36:39], v[32:33], off offset:192
	s_waitcnt vmcnt(3)
	v_mfma_f32_16x16x32_bf16 v[20:23], v[20:23], v[6:9], 0
	s_waitcnt vmcnt(2)
	v_mfma_f32_16x16x32_bf16 v[20:23], v[24:27], v[2:5], v[20:23]
	s_waitcnt vmcnt(1)
	v_mfma_f32_16x16x32_bf16 v[20:23], v[28:31], v[14:17], v[20:23]
	s_waitcnt vmcnt(0)
	v_mfma_f32_16x16x32_bf16 v[102:105], v[36:39], v[10:13], v[20:23]
	s_nop 5
	ds_bpermute_b32 v20, v173, v134
	s_waitcnt lgkmcnt(0)
	v_mad_i64_i32 v[32:33], s[14:15], v20, s62, v[18:19]
	global_load_dwordx4 v[20:23], v[32:33], off
	global_load_dwordx4 v[24:27], v[32:33], off offset:64
	global_load_dwordx4 v[28:31], v[32:33], off offset:128
	global_load_dwordx4 v[36:39], v[32:33], off offset:192
	s_waitcnt vmcnt(3)
	v_mfma_f32_16x16x32_bf16 v[20:23], v[20:23], v[6:9], 0
	s_waitcnt vmcnt(2)
	v_mfma_f32_16x16x32_bf16 v[20:23], v[24:27], v[2:5], v[20:23]
	s_waitcnt vmcnt(1)
	v_mfma_f32_16x16x32_bf16 v[20:23], v[28:31], v[14:17], v[20:23]
	s_waitcnt vmcnt(0)
	v_mfma_f32_16x16x32_bf16 v[106:109], v[36:39], v[10:13], v[20:23]
	s_nop 5
	ds_bpermute_b32 v20, v174, v134
	s_waitcnt lgkmcnt(0)
	v_mad_i64_i32 v[32:33], s[14:15], v20, s62, v[18:19]
	global_load_dwordx4 v[20:23], v[32:33], off
	global_load_dwordx4 v[24:27], v[32:33], off offset:64
	global_load_dwordx4 v[28:31], v[32:33], off offset:128
	global_load_dwordx4 v[36:39], v[32:33], off offset:192
	s_waitcnt vmcnt(3)
	v_mfma_f32_16x16x32_bf16 v[20:23], v[20:23], v[6:9], 0
	s_waitcnt vmcnt(2)
	v_mfma_f32_16x16x32_bf16 v[20:23], v[24:27], v[2:5], v[20:23]
	s_waitcnt vmcnt(1)
	v_mfma_f32_16x16x32_bf16 v[20:23], v[28:31], v[14:17], v[20:23]
	s_waitcnt vmcnt(0)
	v_mfma_f32_16x16x32_bf16 v[110:113], v[36:39], v[10:13], v[20:23]
	s_nop 5
	ds_bpermute_b32 v20, v143, v241
	s_waitcnt lgkmcnt(0)
	v_mad_i64_i32 v[32:33], s[14:15], v20, s62, v[18:19]
	global_load_dwordx4 v[20:23], v[32:33], off
	global_load_dwordx4 v[24:27], v[32:33], off offset:64
	global_load_dwordx4 v[28:31], v[32:33], off offset:128
	global_load_dwordx4 v[36:39], v[32:33], off offset:192
	s_waitcnt vmcnt(3)
	v_mfma_f32_16x16x32_bf16 v[20:23], v[20:23], v[6:9], 0
	s_waitcnt vmcnt(2)
	v_mfma_f32_16x16x32_bf16 v[20:23], v[24:27], v[2:5], v[20:23]
	s_waitcnt vmcnt(1)
	v_mfma_f32_16x16x32_bf16 v[20:23], v[28:31], v[14:17], v[20:23]
	s_waitcnt vmcnt(0)
	v_mfma_f32_16x16x32_bf16 v[114:117], v[36:39], v[10:13], v[20:23]
	s_nop 5
	ds_bpermute_b32 v20, v172, v241
	s_waitcnt lgkmcnt(0)
	v_mad_i64_i32 v[32:33], s[14:15], v20, s62, v[18:19]
	global_load_dwordx4 v[20:23], v[32:33], off
	global_load_dwordx4 v[24:27], v[32:33], off offset:64
	global_load_dwordx4 v[28:31], v[32:33], off offset:128
	global_load_dwordx4 v[36:39], v[32:33], off offset:192
	s_waitcnt vmcnt(3)
	v_mfma_f32_16x16x32_bf16 v[20:23], v[20:23], v[6:9], 0
	s_waitcnt vmcnt(2)
	v_mfma_f32_16x16x32_bf16 v[20:23], v[24:27], v[2:5], v[20:23]
	s_waitcnt vmcnt(1)
	v_mfma_f32_16x16x32_bf16 v[20:23], v[28:31], v[14:17], v[20:23]
	s_waitcnt vmcnt(0)
	v_mfma_f32_16x16x32_bf16 v[118:121], v[36:39], v[10:13], v[20:23]
	s_nop 5
	ds_bpermute_b32 v20, v173, v241
	s_waitcnt lgkmcnt(0)
	v_mad_i64_i32 v[32:33], s[14:15], v20, s62, v[18:19]
	global_load_dwordx4 v[20:23], v[32:33], off
	global_load_dwordx4 v[24:27], v[32:33], off offset:64
	global_load_dwordx4 v[28:31], v[32:33], off offset:128
	global_load_dwordx4 v[36:39], v[32:33], off offset:192
	s_waitcnt vmcnt(3)
	v_mfma_f32_16x16x32_bf16 v[20:23], v[20:23], v[6:9], 0
	s_waitcnt vmcnt(2)
	v_mfma_f32_16x16x32_bf16 v[20:23], v[24:27], v[2:5], v[20:23]
	s_waitcnt vmcnt(1)
	v_mfma_f32_16x16x32_bf16 v[20:23], v[28:31], v[14:17], v[20:23]
	s_waitcnt vmcnt(0)
	v_mfma_f32_16x16x32_bf16 v[122:125], v[36:39], v[10:13], v[20:23]
	s_nop 5
	ds_bpermute_b32 v20, v174, v241
	s_waitcnt lgkmcnt(0)
	v_mad_i64_i32 v[30:31], s[14:15], v20, s62, v[18:19]
	global_load_dwordx4 v[18:21], v[30:31], off
	global_load_dwordx4 v[22:25], v[30:31], off offset:64
	global_load_dwordx4 v[26:29], v[30:31], off offset:128
	s_nop 0
	global_load_dwordx4 v[30:33], v[30:31], off offset:192
	s_waitcnt vmcnt(3)
	v_mfma_f32_16x16x32_bf16 v[6:9], v[18:21], v[6:9], 0
	ds_bpermute_b32 v18, v185, v34
	s_waitcnt vmcnt(2)
	v_mfma_f32_16x16x32_bf16 v[2:5], v[22:25], v[2:5], v[6:9]
	s_waitcnt vmcnt(1)
	v_mfma_f32_16x16x32_bf16 v[2:5], v[26:29], v[14:17], v[2:5]
	s_nop 2
	ds_bpermute_b32 v6, v182, v34
	ds_bpermute_b32 v14, v184, v34
	ds_bpermute_b32 v26, v186, v34
	s_waitcnt vmcnt(0)
; #define ATTN_VLOAD(dst, ks) do { const int sreg_ = ((ks) < 2) ? s0 : ((ks) < 4) ? s1 : ((ks) < 6) ? s2 : s3; _Pragma("unroll") for (int i = 0; i < 8; ++i) { \
;             const int idx_ = shi(sreg_, 32 * ((ks) & 1) + fq + 4 * i); dst[i] = *(const u32x4*)(vbase + (size_t)idx_ * DSA_NP); } } while (0)
; __device__ __forceinline__ void dsa_attn(const bf16_t* DP, const int* SEL, bf16_t* O, LAS unsigned char* lds, int widk) {
;     ...
;         const bf16_t* vbase = DP + (size_t)b * SEQ * DSA_NP + 2560 + g * 128 + fr * 8;
;         u32x4 vcur[8], vnxt[8], vnn[8];
;     ...
;         ATTN_VLOAD(vcur, 0); ATTN_VLOAD(vnxt, 1);
;         float mx = -__builtin_inff();
; #pragma unroll
;         for (int j = 0; j < 16; ++j)
; #pragma unroll
;             for (int r = 0; r < 4; ++r) { const int slot = 16 * j + 4 * fq + r; const float sv = (slot < nvalid) ? acc[j][r] * 0.08838834764831845f : -__builtin_inff(); acc[j][r] = sv; mx = fmaxf(mx, sv); }
	v_mfma_f32_16x16x32_bf16 v[126:129], v[30:33], v[10:13], v[2:5]
	ds_bpermute_b32 v10, v183, v34
	ds_bpermute_b32 v30, v187, v34
	s_nop 0
	v_lshl_add_u64 v[2:3], s[6:7], 0, v[148:149]
	s_mov_b64 s[6:7], 0x1400
	v_lshl_add_u64 v[150:151], v[2:3], 0, s[6:7]
	ds_bpermute_b32 v2, v167, v34
	s_waitcnt lgkmcnt(5)
	v_mad_i64_i32 v[6:7], s[6:7], v6, s62, v[150:151]
	global_load_dwordx4 v[6:9], v[6:7], off
	s_waitcnt lgkmcnt(2)
	v_mad_i64_i32 v[10:11], s[6:7], v10, s62, v[150:151]
	s_waitcnt lgkmcnt(0)
	v_mad_i64_i32 v[2:3], s[6:7], v2, s62, v[150:151]
	global_load_dwordx4 v[22:25], v[2:3], off
	ds_bpermute_b32 v2, v175, v34
	global_load_dwordx4 v[10:13], v[10:11], off
	v_mad_i64_i32 v[14:15], s[6:7], v14, s62, v[150:151]
	global_load_dwordx4 v[14:17], v[14:15], off
	s_waitcnt lgkmcnt(0)
	v_mad_i64_i32 v[2:3], s[6:7], v2, s62, v[150:151]
	global_load_dwordx4 v[38:41], v[2:3], off
	ds_bpermute_b32 v2, v176, v34
	v_mad_i64_i32 v[18:19], s[6:7], v18, s62, v[150:151]
	global_load_dwordx4 v[18:21], v[18:19], off
	v_mad_i64_i32 v[26:27], s[6:7], v26, s62, v[150:151]
	s_waitcnt lgkmcnt(0)
	v_mad_i64_i32 v[2:3], s[6:7], v2, s62, v[150:151]
	global_load_dwordx4 v[42:45], v[2:3], off
	ds_bpermute_b32 v2, v177, v34
	global_load_dwordx4 v[26:29], v[26:27], off
	v_mad_i64_i32 v[30:31], s[6:7], v30, s62, v[150:151]
	global_load_dwordx4 v[30:33], v[30:31], off
	s_waitcnt lgkmcnt(0)
	v_mad_i64_i32 v[2:3], s[6:7], v2, s62, v[150:151]
	global_load_dwordx4 v[46:49], v[2:3], off
	ds_bpermute_b32 v2, v178, v34
	s_waitcnt lgkmcnt(0)
	v_mad_i64_i32 v[2:3], s[6:7], v2, s62, v[150:151]
	global_load_dwordx4 v[50:53], v[2:3], off
	ds_bpermute_b32 v2, v179, v34
	s_waitcnt lgkmcnt(0)
	v_mad_i64_i32 v[2:3], s[6:7], v2, s62, v[150:151]
	global_load_dwordx4 v[54:57], v[2:3], off
	ds_bpermute_b32 v2, v180, v34
	s_waitcnt lgkmcnt(0)
	v_mad_i64_i32 v[2:3], s[6:7], v2, s62, v[150:151]
	global_load_dwordx4 v[58:61], v[2:3], off
	ds_bpermute_b32 v2, v181, v34
	s_waitcnt lgkmcnt(0)
	v_mad_i64_i32 v[2:3], s[6:7], v2, s62, v[150:151]
	global_load_dwordx4 v[62:65], v[2:3], off
	ds_bpermute_b32 v2, v168, v34
	ds_bpermute_b32 v34, v188, v34
	s_waitcnt lgkmcnt(1)
	v_mad_i64_i32 v[2:3], s[6:7], v2, s62, v[150:151]
	s_waitcnt lgkmcnt(0)
	v_mad_i64_i32 v[34:35], s[6:7], v34, s62, v[150:151]
	s_min_i32 s6, s13, 0xff
	s_nop 0
	v_cmp_ge_i32_e32 vcc, s6, v167
	s_mov_b32 s7, 0xff800000
	global_load_dwordx4 v[2:5], v[2:3], off
	v_cndmask_b32_e32 v66, v246, v66, vcc
	v_cmp_gt_i32_e32 vcc, s6, v167
	global_load_dwordx4 v[34:37], v[34:35], off
	s_nop 0
	v_cndmask_b32_e32 v132, v246, v67, vcc
	v_cmp_ge_i32_e32 vcc, s6, v130
	v_max3_f32 v67, v66, s7, v132
	s_nop 0
	v_cndmask_b32_e32 v133, v246, v68, vcc
	v_mul_f32_e32 v68, 0x3db504f3, v69
	v_or_b32_e32 v69, 3, v167
	v_cmp_ge_i32_e32 vcc, s6, v69
	v_or_b32_e32 v69, 17, v167
	s_nop 0
	v_cndmask_b32_e32 v136, v246, v68, vcc
	v_mul_f32_e32 v68, 0x3db504f3, v70
	v_cmp_ge_i32_e32 vcc, s6, v175
	v_max3_f32 v67, v67, v133, v136
	s_nop 0
	v_cndmask_b32_e32 v137, v246, v68, vcc
	v_mul_f32_e32 v68, 0x3db504f3, v71
	v_cmp_ge_i32_e32 vcc, s6, v69
	v_or_b32_e32 v69, 18, v167
	s_nop 0
	v_cndmask_b32_e32 v149, v246, v68, vcc
	v_mul_f32_e32 v68, 0x3db504f3, v72
	v_cmp_ge_i32_e32 vcc, s6, v69
	v_or_b32_e32 v69, 19, v167
	v_max3_f32 v67, v67, v137, v149
	v_cndmask_b32_e32 v190, v246, v68, vcc
	v_mul_f32_e32 v68, 0x3db504f3, v73
	v_cmp_ge_i32_e32 vcc, s6, v69
	v_or_b32_e32 v69, 33, v167
	s_nop 0
	v_cndmask_b32_e32 v191, v246, v68, vcc
	v_mul_f32_e32 v68, 0x3db504f3, v74
	v_cmp_ge_i32_e32 vcc, s6, v176
	v_max3_f32 v67, v67, v190, v191
	s_nop 0
	v_cndmask_b32_e32 v192, v246, v68, vcc
	v_mul_f32_e32 v68, 0x3db504f3, v75
	v_cmp_ge_i32_e32 vcc, s6, v69
	v_or_b32_e32 v69, 34, v167
	s_nop 0
	v_cndmask_b32_e32 v193, v246, v68, vcc
	v_mul_f32_e32 v68, 0x3db504f3, v76
	v_cmp_ge_i32_e32 vcc, s6, v69
	v_or_b32_e32 v69, 35, v167
	v_max3_f32 v67, v67, v192, v193
	v_cndmask_b32_e32 v194, v246, v68, vcc
	v_mul_f32_e32 v68, 0x3db504f3, v77
	v_cmp_ge_i32_e32 vcc, s6, v69
	v_or_b32_e32 v69, 49, v167
	s_nop 0
	v_cndmask_b32_e32 v195, v246, v68, vcc
	v_mul_f32_e32 v68, 0x3db504f3, v78
	v_cmp_ge_i32_e32 vcc, s6, v177
	v_max3_f32 v67, v67, v194, v195
	s_nop 0
	v_cndmask_b32_e32 v196, v246, v68, vcc
	v_mul_f32_e32 v68, 0x3db504f3, v79
	v_cmp_ge_i32_e32 vcc, s6, v69
	v_or_b32_e32 v69, 50, v167
	s_nop 0
	v_cndmask_b32_e32 v197, v246, v68, vcc
	v_mul_f32_e32 v68, 0x3db504f3, v80
	v_cmp_ge_i32_e32 vcc, s6, v69
	v_or_b32_e32 v69, 51, v167
	v_max3_f32 v67, v67, v196, v197
	v_cndmask_b32_e32 v198, v246, v68, vcc
	v_mul_f32_e32 v68, 0x3db504f3, v81
	v_cmp_ge_i32_e32 vcc, s6, v69
	v_or_b32_e32 v69, 0x41, v167
	s_nop 0
	v_cndmask_b32_e32 v199, v246, v68, vcc
	v_mul_f32_e32 v68, 0x3db504f3, v82
	v_cmp_ge_i32_e32 vcc, s6, v178
	v_max3_f32 v67, v67, v198, v199
	s_nop 0
	v_cndmask_b32_e32 v200, v246, v68, vcc
	v_mul_f32_e32 v68, 0x3db504f3, v83
	v_cmp_ge_i32_e32 vcc, s6, v69
	v_or_b32_e32 v69, 0x42, v167
	s_nop 0
	v_cndmask_b32_e32 v201, v246, v68, vcc
	v_mul_f32_e32 v68, 0x3db504f3, v84
	v_cmp_ge_i32_e32 vcc, s6, v69
	v_or_b32_e32 v69, 0x43, v167
	v_max3_f32 v67, v67, v200, v201
	v_cndmask_b32_e32 v202, v246, v68, vcc
	v_mul_f32_e32 v68, 0x3db504f3, v85
	v_cmp_ge_i32_e32 vcc, s6, v69
	v_or_b32_e32 v69, 0x51, v167
	s_nop 0
	v_cndmask_b32_e32 v203, v246, v68, vcc
	v_mul_f32_e32 v68, 0x3db504f3, v86
	v_cmp_ge_i32_e32 vcc, s6, v179
	v_max3_f32 v67, v67, v202, v203
	s_nop 0
	v_cndmask_b32_e32 v204, v246, v68, vcc
	v_mul_f32_e32 v68, 0x3db504f3, v87
	v_cmp_ge_i32_e32 vcc, s6, v69
	v_or_b32_e32 v69, 0x52, v167
	s_nop 0
	v_cndmask_b32_e32 v205, v246, v68, vcc
	v_mul_f32_e32 v68, 0x3db504f3, v88
	v_cmp_ge_i32_e32 vcc, s6, v69
; __device__ __forceinline__ float shx(float v, int m, int lane) { return __int_as_float(__builtin_amdgcn_ds_bpermute((lane ^ m) << 2, __float_as_int(v))); }
; __device__ __forceinline__ void dsa_attn(const bf16_t* DP, const int* SEL, bf16_t* O, LAS unsigned char* lds, int widk) {
;     ...
; #pragma unroll
;         for (int j = 0; j < 16; ++j)
; #pragma unroll
;             for (int r = 0; r < 4; ++r) { const int slot = 16 * j + 4 * fq + r; const float sv = (slot < nvalid) ? acc[j][r] * 0.08838834764831845f : -__builtin_inff(); acc[j][r] = sv; mx = fmaxf(mx, sv); }
;         mx = fmaxf(mx, shx(mx, 16, lane)); mx = fmaxf(mx, shx(mx, 32, lane));
	v_or_b32_e32 v69, 0x53, v167
	v_max3_f32 v67, v67, v204, v205
	v_cndmask_b32_e32 v243, v246, v68, vcc
	v_mul_f32_e32 v68, 0x3db504f3, v89
	v_cmp_ge_i32_e32 vcc, s6, v69
	v_or_b32_e32 v69, 0x61, v167
	s_nop 0
	v_cndmask_b32_e32 v242, v246, v68, vcc
	v_mul_f32_e32 v68, 0x3db504f3, v90
	v_cmp_ge_i32_e32 vcc, s6, v180
	v_max3_f32 v67, v67, v243, v242
	s_nop 0
	v_cndmask_b32_e32 v248, v246, v68, vcc
	v_mul_f32_e32 v68, 0x3db504f3, v91
	v_cmp_ge_i32_e32 vcc, s6, v69
	v_or_b32_e32 v69, 0x62, v167
	s_nop 0
	v_cndmask_b32_e32 v189, v246, v68, vcc
	v_mul_f32_e32 v68, 0x3db504f3, v92
	v_cmp_ge_i32_e32 vcc, s6, v69
	v_or_b32_e32 v69, 0x63, v167
	v_max3_f32 v67, v67, v248, v189
	v_cndmask_b32_e32 v206, v246, v68, vcc
	v_mul_f32_e32 v68, 0x3db504f3, v93
	v_cmp_ge_i32_e32 vcc, s6, v69
	v_or_b32_e32 v69, 0x71, v167
	s_nop 0
	v_cndmask_b32_e32 v207, v246, v68, vcc
	v_mul_f32_e32 v68, 0x3db504f3, v94
	v_cmp_ge_i32_e32 vcc, s6, v181
	v_max3_f32 v67, v67, v206, v207
	s_nop 0
	v_cndmask_b32_e32 v208, v246, v68, vcc
	v_mul_f32_e32 v68, 0x3db504f3, v95
	v_cmp_ge_i32_e32 vcc, s6, v69
	v_or_b32_e32 v69, 0x72, v167
	s_nop 0
	v_cndmask_b32_e32 v209, v246, v68, vcc
	v_mul_f32_e32 v68, 0x3db504f3, v96
	v_cmp_ge_i32_e32 vcc, s6, v69
	v_or_b32_e32 v69, 0x73, v167
	v_max3_f32 v67, v67, v208, v209
	v_cndmask_b32_e32 v210, v246, v68, vcc
	v_mul_f32_e32 v68, 0x3db504f3, v97
	v_cmp_ge_i32_e32 vcc, s6, v69
	v_or_b32_e32 v69, 0x81, v167
	s_nop 0
	v_cndmask_b32_e32 v211, v246, v68, vcc
	v_mul_f32_e32 v68, 0x3db504f3, v98
	v_cmp_ge_i32_e32 vcc, s6, v168
	v_max3_f32 v67, v67, v210, v211
	s_nop 0
	v_cndmask_b32_e32 v212, v246, v68, vcc
	v_mul_f32_e32 v68, 0x3db504f3, v99
	v_cmp_ge_i32_e32 vcc, s6, v69
	v_or_b32_e32 v69, 0x82, v167
	s_nop 0
	v_cndmask_b32_e32 v213, v246, v68, vcc
	v_mul_f32_e32 v68, 0x3db504f3, v100
	v_cmp_ge_i32_e32 vcc, s6, v69
	v_or_b32_e32 v69, 0x83, v167
	v_max3_f32 v67, v67, v212, v213
	v_cndmask_b32_e32 v214, v246, v68, vcc
	v_mul_f32_e32 v68, 0x3db504f3, v101
	v_cmp_ge_i32_e32 vcc, s6, v69
	v_or_b32_e32 v69, 0x91, v167
	s_nop 0
	v_cndmask_b32_e32 v215, v246, v68, vcc
	v_mul_f32_e32 v68, 0x3db504f3, v102
	v_cmp_ge_i32_e32 vcc, s6, v182
	v_max3_f32 v67, v67, v214, v215
	s_nop 0
	v_cndmask_b32_e32 v216, v246, v68, vcc
	v_mul_f32_e32 v68, 0x3db504f3, v103
	v_cmp_ge_i32_e32 vcc, s6, v69
	s_nop 1
	v_cndmask_b32_e32 v217, v246, v68, vcc
	v_mul_f32_e32 v68, 0x3db504f3, v104
	v_cmp_ge_i32_e32 vcc, s6, v220
	v_max3_f32 v67, v67, v216, v217
	s_nop 0
	v_cndmask_b32_e32 v218, v246, v68, vcc
	v_mul_f32_e32 v68, 0x3db504f3, v105
	v_cmp_ge_i32_e32 vcc, s6, v221
	s_nop 1
	v_cndmask_b32_e32 v219, v246, v68, vcc
	v_mul_f32_e32 v68, 0x3db504f3, v106
	v_cmp_ge_i32_e32 vcc, s6, v183
	v_max3_f32 v67, v67, v218, v219
	s_nop 0
	v_cndmask_b32_e32 v131, v246, v68, vcc
	v_mul_f32_e32 v68, 0x3db504f3, v107
	v_cmp_ge_i32_e32 vcc, s6, v222
	s_nop 1
	v_cndmask_b32_e32 v130, v246, v68, vcc
	v_mul_f32_e32 v68, 0x3db504f3, v108
	v_cmp_ge_i32_e32 vcc, s6, v223
	v_max3_f32 v67, v67, v131, v130
	s_nop 0
	v_cndmask_b32_e32 v107, v246, v68, vcc
	v_mul_f32_e32 v68, 0x3db504f3, v109
	v_cmp_ge_i32_e32 vcc, s6, v224
	s_nop 1
	v_cndmask_b32_e32 v105, v246, v68, vcc
	v_mul_f32_e32 v68, 0x3db504f3, v110
	v_cmp_ge_i32_e32 vcc, s6, v184
	v_max3_f32 v67, v67, v107, v105
	s_nop 0
	v_cndmask_b32_e32 v103, v246, v68, vcc
	v_mul_f32_e32 v68, 0x3db504f3, v111
	v_cmp_ge_i32_e32 vcc, s6, v225
	s_nop 1
	v_cndmask_b32_e32 v101, v246, v68, vcc
	v_mul_f32_e32 v68, 0x3db504f3, v112
	v_cmp_ge_i32_e32 vcc, s6, v226
	v_max3_f32 v67, v67, v103, v101
	s_nop 0
	v_cndmask_b32_e32 v100, v246, v68, vcc
	v_mul_f32_e32 v68, 0x3db504f3, v113
	v_cmp_ge_i32_e32 vcc, s6, v227
	s_nop 1
	v_cndmask_b32_e32 v98, v246, v68, vcc
	v_mul_f32_e32 v68, 0x3db504f3, v114
	v_cmp_ge_i32_e32 vcc, s6, v185
	v_max3_f32 v67, v67, v100, v98
	s_nop 0
	v_cndmask_b32_e32 v95, v246, v68, vcc
	v_mul_f32_e32 v68, 0x3db504f3, v115
	v_cmp_ge_i32_e32 vcc, s6, v228
	s_nop 1
	v_cndmask_b32_e32 v94, v246, v68, vcc
	v_mul_f32_e32 v68, 0x3db504f3, v116
	v_cmp_ge_i32_e32 vcc, s6, v229
	v_max3_f32 v67, v67, v95, v94
	s_nop 0
	v_cndmask_b32_e32 v92, v246, v68, vcc
	v_mul_f32_e32 v68, 0x3db504f3, v117
	v_cmp_ge_i32_e32 vcc, s6, v230
	s_nop 1
	v_cndmask_b32_e32 v91, v246, v68, vcc
	v_mul_f32_e32 v68, 0x3db504f3, v118
	v_cmp_ge_i32_e32 vcc, s6, v186
	v_max3_f32 v67, v67, v92, v91
	s_nop 0
	v_cndmask_b32_e32 v88, v246, v68, vcc
	v_mul_f32_e32 v68, 0x3db504f3, v119
	v_cmp_ge_i32_e32 vcc, s6, v231
	s_nop 1
	v_cndmask_b32_e32 v86, v246, v68, vcc
	v_mul_f32_e32 v68, 0x3db504f3, v120
	v_cmp_ge_i32_e32 vcc, s6, v232
	v_max3_f32 v67, v67, v88, v86
	s_nop 0
	v_cndmask_b32_e32 v85, v246, v68, vcc
	v_mul_f32_e32 v68, 0x3db504f3, v121
	v_cmp_ge_i32_e32 vcc, s6, v233
	s_nop 1
	v_cndmask_b32_e32 v83, v246, v68, vcc
	v_mul_f32_e32 v68, 0x3db504f3, v122
	v_cmp_ge_i32_e32 vcc, s6, v187
	v_max3_f32 v67, v67, v85, v83
	s_nop 0
	v_cndmask_b32_e32 v81, v246, v68, vcc
	v_mul_f32_e32 v68, 0x3db504f3, v123
	v_cmp_ge_i32_e32 vcc, s6, v234
	s_nop 1
	v_cndmask_b32_e32 v79, v246, v68, vcc
	v_mul_f32_e32 v68, 0x3db504f3, v124
	v_cmp_ge_i32_e32 vcc, s6, v235
	v_max3_f32 v67, v67, v81, v79
	s_nop 0
	v_cndmask_b32_e32 v76, v246, v68, vcc
	v_mul_f32_e32 v68, 0x3db504f3, v125
	v_cmp_ge_i32_e32 vcc, s6, v236
	s_nop 1
	v_cndmask_b32_e32 v75, v246, v68, vcc
	v_mul_f32_e32 v68, 0x3db504f3, v126
	v_cmp_ge_i32_e32 vcc, s6, v188
	v_max3_f32 v67, v67, v76, v75
	s_nop 0
	v_cndmask_b32_e32 v72, v246, v68, vcc
	v_mul_f32_e32 v68, 0x3db504f3, v127
	v_cmp_ge_i32_e32 vcc, s6, v237
	s_nop 1
	v_cndmask_b32_e32 v71, v246, v68, vcc
	v_max3_f32 v68, v67, v72, v71
	v_mul_f32_e32 v67, 0x3db504f3, v128
	v_cmp_ge_i32_e32 vcc, s6, v238
	s_nop 1
	v_cndmask_b32_e32 v69, v246, v67, vcc
	v_mul_f32_e32 v67, 0x3db504f3, v129
	v_cmp_ge_i32_e32 vcc, s6, v239
	s_nop 1
	v_cndmask_b32_e32 v67, v246, v67, vcc
	v_max3_f32 v68, v68, v69, v67
	ds_bpermute_b32 v70, v169, v68
	s_waitcnt lgkmcnt(0)
; __device__ __forceinline__ float shx(float v, int m, int lane) { return __int_as_float(__builtin_amdgcn_ds_bpermute((lane ^ m) << 2, __float_as_int(v))); }
; __device__ __forceinline__ void dsa_attn(const bf16_t* DP, const int* SEL, bf16_t* O, LAS unsigned char* lds, int widk) {
;     ...
;         mx = fmaxf(mx, shx(mx, 16, lane)); mx = fmaxf(mx, shx(mx, 32, lane));
;         float sum = 0.f;
; #pragma unroll
;         for (int j = 0; j < 16; ++j)
; #pragma unroll
;             for (int r = 0; r < 4; ++r) { const float pv = __expf(acc[j][r] - mx); acc[j][r] = pv; sum += pv; }
	v_max_f32_e32 v70, v70, v70
	v_max_f32_e32 v68, v68, v70
	ds_bpermute_b32 v70, v170, v68
	s_waitcnt lgkmcnt(0)
	v_max_f32_e32 v70, v70, v70
	v_max_f32_e32 v78, v68, v70
	v_sub_f32_e32 v66, v66, v78
	v_mul_f32_e32 v66, 0x3fb8aa3b, v66
	v_sub_f32_e32 v68, v132, v78
	v_exp_f32_e32 v66, v66
	v_mul_f32_e32 v68, 0x3fb8aa3b, v68
	v_exp_f32_e32 v68, v68
	v_sub_f32_e32 v130, v130, v78
	v_add_f32_e32 v70, 0, v66
	v_mul_f32_e32 v130, 0x3fb8aa3b, v130
	v_add_f32_e32 v73, v68, v70
	v_sub_f32_e32 v70, v133, v78
	v_mul_f32_e32 v70, 0x3fb8aa3b, v70
	v_exp_f32_e32 v70, v70
	v_sub_f32_e32 v107, v107, v78
	v_exp_f32_e32 v130, v130
	v_mul_f32_e32 v107, 0x3fb8aa3b, v107
	v_add_f32_e32 v74, v70, v73
	v_sub_f32_e32 v73, v136, v78
	v_mul_f32_e32 v73, 0x3fb8aa3b, v73
	v_exp_f32_e32 v73, v73
	v_sub_f32_e32 v105, v105, v78
	v_exp_f32_e32 v107, v107
	v_mul_f32_e32 v105, 0x3fb8aa3b, v105
	v_add_f32_e32 v77, v73, v74
	v_sub_f32_e32 v74, v137, v78
	v_mul_f32_e32 v74, 0x3fb8aa3b, v74
	v_exp_f32_e32 v74, v74
	v_sub_f32_e32 v103, v103, v78
	v_exp_f32_e32 v105, v105
	v_mul_f32_e32 v103, 0x3fb8aa3b, v103
	v_add_f32_e32 v80, v74, v77
	v_sub_f32_e32 v77, v149, v78
	v_mul_f32_e32 v77, 0x3fb8aa3b, v77
	v_exp_f32_e32 v77, v77
	v_sub_f32_e32 v101, v101, v78
	v_exp_f32_e32 v103, v103
	v_mul_f32_e32 v101, 0x3fb8aa3b, v101
	v_add_f32_e32 v82, v77, v80
	v_sub_f32_e32 v80, v190, v78
	v_mul_f32_e32 v80, 0x3fb8aa3b, v80
	v_exp_f32_e32 v80, v80
	v_sub_f32_e32 v100, v100, v78
	v_exp_f32_e32 v101, v101
	v_mul_f32_e32 v100, 0x3fb8aa3b, v100
	v_add_f32_e32 v84, v80, v82
	v_sub_f32_e32 v82, v191, v78
	v_mul_f32_e32 v82, 0x3fb8aa3b, v82
	v_exp_f32_e32 v82, v82
	v_sub_f32_e32 v98, v98, v78
	v_exp_f32_e32 v100, v100
	v_mul_f32_e32 v98, 0x3fb8aa3b, v98
	v_add_f32_e32 v87, v82, v84
	v_sub_f32_e32 v84, v192, v78
	v_mul_f32_e32 v84, 0x3fb8aa3b, v84
	v_exp_f32_e32 v84, v84
	v_sub_f32_e32 v95, v95, v78
	v_exp_f32_e32 v98, v98
	v_mul_f32_e32 v95, 0x3fb8aa3b, v95
	v_add_f32_e32 v89, v84, v87
	v_sub_f32_e32 v87, v193, v78
	v_mul_f32_e32 v87, 0x3fb8aa3b, v87
	v_exp_f32_e32 v87, v87
	v_sub_f32_e32 v94, v94, v78
	v_exp_f32_e32 v95, v95
	v_mul_f32_e32 v94, 0x3fb8aa3b, v94
	v_add_f32_e32 v90, v87, v89
	v_sub_f32_e32 v89, v194, v78
	v_mul_f32_e32 v89, 0x3fb8aa3b, v89
	v_exp_f32_e32 v89, v89
	v_sub_f32_e32 v92, v92, v78
	v_exp_f32_e32 v94, v94
	v_mul_f32_e32 v92, 0x3fb8aa3b, v92
	v_add_f32_e32 v93, v89, v90
	v_sub_f32_e32 v90, v195, v78
	v_mul_f32_e32 v90, 0x3fb8aa3b, v90
	v_exp_f32_e32 v90, v90
	v_sub_f32_e32 v91, v91, v78
	v_exp_f32_e32 v92, v92
	v_mul_f32_e32 v91, 0x3fb8aa3b, v91
	v_add_f32_e32 v96, v90, v93
	v_sub_f32_e32 v93, v196, v78
	v_mul_f32_e32 v93, 0x3fb8aa3b, v93
	v_exp_f32_e32 v93, v93
	v_sub_f32_e32 v88, v88, v78
	v_exp_f32_e32 v91, v91
	v_mul_f32_e32 v88, 0x3fb8aa3b, v88
	v_add_f32_e32 v97, v93, v96
	v_sub_f32_e32 v96, v197, v78
	v_mul_f32_e32 v96, 0x3fb8aa3b, v96
	v_exp_f32_e32 v96, v96
	v_sub_f32_e32 v86, v86, v78
	v_exp_f32_e32 v88, v88
	v_mul_f32_e32 v86, 0x3fb8aa3b, v86
	v_add_f32_e32 v99, v96, v97
	v_sub_f32_e32 v97, v198, v78
	v_mul_f32_e32 v97, 0x3fb8aa3b, v97
	v_exp_f32_e32 v97, v97
	v_sub_f32_e32 v85, v85, v78
	v_exp_f32_e32 v86, v86
	v_mul_f32_e32 v85, 0x3fb8aa3b, v85
	v_add_f32_e32 v102, v97, v99
	v_sub_f32_e32 v99, v199, v78
	v_mul_f32_e32 v99, 0x3fb8aa3b, v99
	v_exp_f32_e32 v99, v99
	v_sub_f32_e32 v83, v83, v78
	v_exp_f32_e32 v85, v85
	v_mul_f32_e32 v83, 0x3fb8aa3b, v83
	v_add_f32_e32 v104, v99, v102
	v_sub_f32_e32 v102, v200, v78
	v_mul_f32_e32 v102, 0x3fb8aa3b, v102
	v_exp_f32_e32 v102, v102
	v_sub_f32_e32 v81, v81, v78
	v_exp_f32_e32 v83, v83
	v_mul_f32_e32 v81, 0x3fb8aa3b, v81
	v_add_f32_e32 v106, v102, v104
	v_sub_f32_e32 v104, v201, v78
	v_mul_f32_e32 v104, 0x3fb8aa3b, v104
	v_exp_f32_e32 v104, v104
	v_sub_f32_e32 v79, v79, v78
	v_exp_f32_e32 v81, v81
	v_mul_f32_e32 v79, 0x3fb8aa3b, v79
	v_add_f32_e32 v108, v104, v106
	v_sub_f32_e32 v106, v202, v78
	v_mul_f32_e32 v106, 0x3fb8aa3b, v106
	v_exp_f32_e32 v106, v106
	v_sub_f32_e32 v76, v76, v78
	v_exp_f32_e32 v79, v79
	v_mul_f32_e32 v76, 0x3fb8aa3b, v76
	v_add_f32_e32 v109, v106, v108
	v_sub_f32_e32 v108, v203, v78
	v_mul_f32_e32 v108, 0x3fb8aa3b, v108
	v_exp_f32_e32 v108, v108
	v_sub_f32_e32 v75, v75, v78
	v_exp_f32_e32 v76, v76
	v_mul_f32_e32 v75, 0x3fb8aa3b, v75
	v_add_f32_e32 v110, v108, v109
	v_sub_f32_e32 v109, v204, v78
	v_mul_f32_e32 v109, 0x3fb8aa3b, v109
	v_exp_f32_e32 v109, v109
	v_sub_f32_e32 v72, v72, v78
	v_exp_f32_e32 v75, v75
	v_mul_f32_e32 v72, 0x3fb8aa3b, v72
	v_add_f32_e32 v111, v109, v110
	v_sub_f32_e32 v110, v205, v78
	v_mul_f32_e32 v110, 0x3fb8aa3b, v110
	v_exp_f32_e32 v110, v110
	v_sub_f32_e32 v71, v71, v78
	v_exp_f32_e32 v72, v72
	v_mul_f32_e32 v71, 0x3fb8aa3b, v71
	v_add_f32_e32 v112, v110, v111
	v_sub_f32_e32 v111, v243, v78
	v_mul_f32_e32 v111, 0x3fb8aa3b, v111
	v_exp_f32_e32 v111, v111
	v_sub_f32_e32 v69, v69, v78
	v_exp_f32_e32 v71, v71
	v_mul_f32_e32 v69, 0x3fb8aa3b, v69
	v_add_f32_e32 v113, v111, v112
	v_sub_f32_e32 v112, v242, v78
	v_mul_f32_e32 v112, 0x3fb8aa3b, v112
	v_exp_f32_e32 v112, v112
	v_sub_f32_e32 v67, v67, v78
	v_exp_f32_e32 v69, v69
	v_mul_f32_e32 v67, 0x3fb8aa3b, v67
	v_add_f32_e32 v114, v112, v113
	v_sub_f32_e32 v113, v248, v78
	v_mul_f32_e32 v113, 0x3fb8aa3b, v113
	v_exp_f32_e32 v113, v113
	v_exp_f32_e32 v67, v67
	v_add_f32_e32 v115, v113, v114
	v_sub_f32_e32 v114, v189, v78
	v_mul_f32_e32 v114, 0x3fb8aa3b, v114
	v_exp_f32_e32 v114, v114
	s_nop 0
	v_add_f32_e32 v116, v114, v115
	v_sub_f32_e32 v115, v206, v78
	v_mul_f32_e32 v115, 0x3fb8aa3b, v115
	v_exp_f32_e32 v115, v115
	s_nop 0
	v_add_f32_e32 v117, v115, v116
	v_sub_f32_e32 v116, v207, v78
	v_mul_f32_e32 v116, 0x3fb8aa3b, v116
; #define LAS __attribute__((address_space(3)))
; __device__ __forceinline__ unsigned cvt_pk_bf16(float lo, float hi) { unsigned r; asm volatile("v_cvt_pk_bf16_f32 %0, %1, %2" : "=v"(r) : "v"(lo), "v"(hi)); return r; }
; __device__ __forceinline__ float shx(float v, int m, int lane) { return __int_as_float(__builtin_amdgcn_ds_bpermute((lane ^ m) << 2, __float_as_int(v))); }
; __device__ __forceinline__ void dsa_attn(const bf16_t* DP, const int* SEL, bf16_t* O, LAS unsigned char* lds, int widk) {
;     ...
;         for (int j = 0; j < 16; ++j)
; #pragma unroll
;             for (int r = 0; r < 4; ++r) { const float pv = __expf(acc[j][r] - mx); acc[j][r] = pv; sum += pv; }
;         sum += shx(sum, 16, lane); sum += shx(sum, 32, lane);
;         const float inv = 1.0f / sum;
;         if (fr < 4) {
; #pragma unroll
;             for (int j = 0; j < 16; ++j) { u32x2 w; w.x = cvt_pk_bf16(acc[j][0] * inv, acc[j][1] * inv); w.y = cvt_pk_bf16(acc[j][2] * inv, acc[j][3] * inv);
;                 *(LAS u32x2*)(pl + (fr * 256 + 16 * j + 4 * fq) * 2) = w; }
;         }
	v_exp_f32_e32 v116, v116
	s_nop 0
	v_add_f32_e32 v118, v116, v117
	v_sub_f32_e32 v117, v208, v78
	v_mul_f32_e32 v117, 0x3fb8aa3b, v117
	v_exp_f32_e32 v117, v117
	s_nop 0
	v_add_f32_e32 v119, v117, v118
	v_sub_f32_e32 v118, v209, v78
	v_mul_f32_e32 v118, 0x3fb8aa3b, v118
	v_exp_f32_e32 v118, v118
	s_nop 0
	v_add_f32_e32 v120, v118, v119
	v_sub_f32_e32 v119, v210, v78
	v_mul_f32_e32 v119, 0x3fb8aa3b, v119
	v_exp_f32_e32 v119, v119
	s_nop 0
	v_add_f32_e32 v121, v119, v120
	v_sub_f32_e32 v120, v211, v78
	v_mul_f32_e32 v120, 0x3fb8aa3b, v120
	v_exp_f32_e32 v120, v120
	s_nop 0
	v_add_f32_e32 v122, v120, v121
	v_sub_f32_e32 v121, v212, v78
	v_mul_f32_e32 v121, 0x3fb8aa3b, v121
	v_exp_f32_e32 v121, v121
	s_nop 0
	v_add_f32_e32 v123, v121, v122
	v_sub_f32_e32 v122, v213, v78
	v_mul_f32_e32 v122, 0x3fb8aa3b, v122
	v_exp_f32_e32 v122, v122
	s_nop 0
	v_add_f32_e32 v124, v122, v123
	v_sub_f32_e32 v123, v214, v78
	v_mul_f32_e32 v123, 0x3fb8aa3b, v123
	v_exp_f32_e32 v123, v123
	s_nop 0
	v_add_f32_e32 v125, v123, v124
	v_sub_f32_e32 v124, v215, v78
	v_mul_f32_e32 v124, 0x3fb8aa3b, v124
	v_exp_f32_e32 v124, v124
	s_nop 0
	v_add_f32_e32 v126, v124, v125
	v_sub_f32_e32 v125, v216, v78
	v_mul_f32_e32 v125, 0x3fb8aa3b, v125
	v_exp_f32_e32 v125, v125
	s_nop 0
	v_add_f32_e32 v127, v125, v126
	v_sub_f32_e32 v126, v217, v78
	v_mul_f32_e32 v126, 0x3fb8aa3b, v126
	v_exp_f32_e32 v126, v126
	s_nop 0
	v_add_f32_e32 v128, v126, v127
	v_sub_f32_e32 v127, v218, v78
	v_mul_f32_e32 v127, 0x3fb8aa3b, v127
	v_exp_f32_e32 v127, v127
	s_nop 0
	v_add_f32_e32 v129, v127, v128
	v_sub_f32_e32 v128, v219, v78
	v_mul_f32_e32 v128, 0x3fb8aa3b, v128
	v_exp_f32_e32 v128, v128
	s_nop 0
	v_add_f32_e32 v132, v128, v129
	v_sub_f32_e32 v129, v131, v78
	v_mul_f32_e32 v129, 0x3fb8aa3b, v129
	v_exp_f32_e32 v129, v129
	s_nop 0
	v_add_f32_e32 v131, v129, v132
	v_add_f32_e32 v131, v130, v131
	v_add_f32_e32 v131, v107, v131
	v_add_f32_e32 v131, v105, v131
	v_add_f32_e32 v131, v103, v131
	v_add_f32_e32 v131, v101, v131
	v_add_f32_e32 v131, v100, v131
	v_add_f32_e32 v131, v98, v131
	v_add_f32_e32 v131, v95, v131
	v_add_f32_e32 v131, v94, v131
	v_add_f32_e32 v131, v92, v131
	v_add_f32_e32 v131, v91, v131
	v_add_f32_e32 v131, v88, v131
	v_add_f32_e32 v131, v86, v131
	v_add_f32_e32 v131, v85, v131
	v_add_f32_e32 v131, v83, v131
	v_add_f32_e32 v131, v81, v131
	v_add_f32_e32 v131, v79, v131
	v_add_f32_e32 v131, v76, v131
	v_add_f32_e32 v131, v75, v131
	v_add_f32_e32 v131, v72, v131
	v_add_f32_e32 v131, v71, v131
	v_add_f32_e32 v131, v69, v131
	v_add_f32_e32 v78, v67, v131
	ds_bpermute_b32 v131, v169, v78
	s_waitcnt lgkmcnt(0)
	v_add_f32_e32 v78, v78, v131
	ds_bpermute_b32 v131, v170, v78
	s_and_saveexec_b64 s[6:7], s[0:1]
	s_cbranch_execz .LBB0_673
	s_waitcnt lgkmcnt(0)
	v_add_f32_e32 v78, v78, v131
	v_div_scale_f32 v131, s[14:15], v78, v78, 1.0
	v_rcp_f32_e32 v132, v131
	v_div_scale_f32 v133, vcc, 1.0, v78, 1.0
	v_fma_f32 v136, -v131, v132, 1.0
	v_fmac_f32_e32 v132, v136, v132
	v_mul_f32_e32 v136, v133, v132
	v_fma_f32 v137, -v131, v136, v133
	v_fmac_f32_e32 v136, v137, v132
	v_fma_f32 v131, -v131, v136, v133
	v_div_fmas_f32 v131, v131, v132, v136
	v_div_fixup_f32 v78, v131, v78, 1.0
	v_mul_f32_e32 v66, v66, v78
	v_mul_f32_e32 v68, v68, v78
	v_cvt_pk_bf16_f32 v132, v66, v68
	v_mul_f32_e32 v66, v70, v78
	v_mul_f32_e32 v68, v73, v78
	v_cvt_pk_bf16_f32 v133, v66, v68
	v_add_u32_e32 v68, v171, v138
	v_mul_f32_e32 v66, v74, v78
	ds_write_b64 v68, v[132:133]
	v_mul_f32_e32 v70, v77, v78
	v_cvt_pk_bf16_f32 v132, v66, v70
	v_mul_f32_e32 v66, v80, v78
	v_mul_f32_e32 v70, v82, v78
	v_cvt_pk_bf16_f32 v133, v66, v70
	v_mul_f32_e32 v66, v84, v78
	ds_write_b64 v68, v[132:133] offset:32
	v_mul_f32_e32 v70, v87, v78
	v_cvt_pk_bf16_f32 v132, v66, v70
	v_mul_f32_e32 v66, v89, v78
	v_mul_f32_e32 v70, v90, v78
	v_cvt_pk_bf16_f32 v133, v66, v70
	v_mul_f32_e32 v66, v93, v78
	ds_write_b64 v68, v[132:133] offset:64
	v_mul_f32_e32 v70, v96, v78
	v_cvt_pk_bf16_f32 v96, v66, v70
	v_mul_f32_e32 v66, v97, v78
	v_mul_f32_e32 v70, v99, v78
	v_cvt_pk_bf16_f32 v97, v66, v70
	v_mul_f32_e32 v66, v102, v78
	ds_write_b64 v68, v[96:97] offset:96
	v_mul_f32_e32 v70, v104, v78
	v_cvt_pk_bf16_f32 v96, v66, v70
	v_mul_f32_e32 v66, v106, v78
	v_mul_f32_e32 v70, v108, v78
	v_cvt_pk_bf16_f32 v97, v66, v70
	v_mul_f32_e32 v66, v109, v78
	ds_write_b64 v68, v[96:97] offset:128
	v_mul_f32_e32 v70, v110, v78
	v_cvt_pk_bf16_f32 v96, v66, v70
	v_mul_f32_e32 v66, v111, v78
	v_mul_f32_e32 v70, v112, v78
	v_cvt_pk_bf16_f32 v97, v66, v70
	v_mul_f32_e32 v66, v113, v78
	ds_write_b64 v68, v[96:97] offset:160
	v_mul_f32_e32 v70, v114, v78
	v_cvt_pk_bf16_f32 v96, v66, v70
	v_mul_f32_e32 v66, v115, v78
	v_mul_f32_e32 v70, v116, v78
	v_cvt_pk_bf16_f32 v97, v66, v70
	v_mul_f32_e32 v66, v117, v78
	ds_write_b64 v68, v[96:97] offset:192
	v_mul_f32_e32 v70, v118, v78
	v_cvt_pk_bf16_f32 v96, v66, v70
	v_mul_f32_e32 v66, v119, v78
	v_mul_f32_e32 v70, v120, v78
	v_cvt_pk_bf16_f32 v97, v66, v70
	v_mul_f32_e32 v66, v121, v78
	ds_write_b64 v68, v[96:97] offset:224
	v_mul_f32_e32 v70, v122, v78
	v_cvt_pk_bf16_f32 v96, v66, v70
	v_mul_f32_e32 v66, v123, v78
	v_mul_f32_e32 v70, v124, v78
	v_cvt_pk_bf16_f32 v97, v66, v70
	v_mul_f32_e32 v66, v125, v78
	ds_write_b64 v68, v[96:97] offset:256
	v_mul_f32_e32 v70, v126, v78
	v_cvt_pk_bf16_f32 v96, v66, v70
	v_mul_f32_e32 v66, v127, v78
	v_mul_f32_e32 v70, v128, v78
	v_cvt_pk_bf16_f32 v97, v66, v70
	v_mul_f32_e32 v66, v129, v78
	ds_write_b64 v68, v[96:97] offset:288
	v_mul_f32_e32 v70, v130, v78
	v_cvt_pk_bf16_f32 v96, v66, v70
	v_mul_f32_e32 v66, v107, v78
	v_mul_f32_e32 v70, v105, v78
	v_cvt_pk_bf16_f32 v97, v66, v70
	v_mul_f32_e32 v66, v103, v78
	ds_write_b64 v68, v[96:97] offset:320
	v_mul_f32_e32 v70, v101, v78
	v_cvt_pk_bf16_f32 v96, v66, v70
	v_mul_f32_e32 v66, v100, v78
	v_mul_f32_e32 v70, v98, v78
	v_cvt_pk_bf16_f32 v97, v66, v70
	v_mul_f32_e32 v66, v95, v78
	ds_write_b64 v68, v[96:97] offset:352
	v_mul_f32_e32 v70, v94, v78
	v_cvt_pk_bf16_f32 v90, v66, v70
	v_mul_f32_e32 v66, v92, v78
	v_mul_f32_e32 v70, v91, v78
	v_cvt_pk_bf16_f32 v91, v66, v70
	v_mul_f32_e32 v66, v88, v78
	ds_write_b64 v68, v[90:91] offset:384
	v_mul_f32_e32 v70, v86, v78
	v_cvt_pk_bf16_f32 v82, v66, v70
	v_mul_f32_e32 v66, v85, v78
	v_mul_f32_e32 v70, v83, v78
	v_cvt_pk_bf16_f32 v83, v66, v70
	v_mul_f32_e32 v66, v81, v78
	ds_write_b64 v68, v[82:83] offset:416
	v_mul_f32_e32 v70, v79, v78
	v_cvt_pk_bf16_f32 v74, v66, v70
	v_mul_f32_e32 v66, v76, v78
	v_mul_f32_e32 v70, v75, v78
	v_cvt_pk_bf16_f32 v75, v66, v70
	v_mul_f32_e32 v66, v72, v78
	v_mul_f32_e32 v67, v67, v78
	ds_write_b64 v68, v[74:75] offset:448
	v_mul_f32_e32 v70, v71, v78
	v_cvt_pk_bf16_f32 v66, v66, v70
	v_mul_f32_e32 v69, v69, v78
	v_cvt_pk_bf16_f32 v67, v69, v67
	ds_write_b64 v68, v[66:67] offset:480
